# attention: MFMA-to-VALU hazard pad moved from the first P.V gap to just after the last QK MFMA (same formal wait states)
# baseline (speedup 1.0000x reference)
.LBB0_185:
	ds_read_b128 v[126:129], v244 offset:16384
	s_waitcnt lgkmcnt(1)
	v_mfma_f32_32x32x16_bf16 v[82:97], v[202:205], v[146:149], v[66:81]
	ds_read_b128 v[122:125], v240 offset:24576
	v_mfma_f32_32x32x16_bf16 v[98:113], v[194:197], v[146:149], v[66:81]
	ds_read_b128 v[114:117], v241 offset:16384
	v_mfma_f32_32x32x16_bf16 v[82:97], v[198:201], v[150:153], v[82:97]
	ds_read_b128 v[118:121], v241 offset:24576
	s_waitcnt lgkmcnt(0)
	v_mfma_f32_32x32x16_bf16 v[98:113], v[122:125], v[150:153], v[98:113]
	ds_read_b128 v[122:125], v243 offset:16384
	v_mfma_f32_32x32x16_bf16 v[82:97], v[114:117], v[154:157], v[82:97]
	ds_read_b128 v[114:117], v243 offset:24576
	v_mfma_f32_32x32x16_bf16 v[98:113], v[118:121], v[154:157], v[98:113]
	s_waitcnt lgkmcnt(0)
	v_mfma_f32_32x32x16_bf16 v[82:97], v[122:125], v[158:161], v[82:97]
	v_mfma_f32_32x32x16_bf16 v[98:113], v[114:117], v[158:161], v[98:113]
	s_nop 1
	ds_read_b128 v[122:125], v244 offset:20480
	ds_read_b128 v[118:121], v244 offset:24576
	ds_read_b128 v[114:117], v244 offset:28672
	s_add_i32 s22, s21, 64
	s_cmp_le_u32 s22, s20
	s_cbranch_scc0 .Lnear_u1e
.LBB0_188:
	v_mfma_f32_32x32x16_bf16 v[34:49], v[126:129], v[162:165], v[34:49]
	ds_read_b128 v[126:129], v245 offset:16384
	v_exp_f32_e32 v130, v82
	v_exp_f32_e32 v131, v83
	v_add_f32_e32 v132, v1, v130
	v_add_f32_e32 v133, v1, v131
	v_cvt_pk_bf16_f32 v166, v130, v131
	s_waitcnt lgkmcnt(3)
	v_mfma_f32_32x32x16_bf16 v[50:65], v[122:125], v[162:165], v[50:65]
	ds_read_b128 v[122:125], v245 offset:20480
	v_exp_f32_e32 v134, v84
	v_exp_f32_e32 v135, v85
	s_add_i32 s22, s23, 2
	v_add_f32_e32 v130, v132, v134
	v_add_f32_e32 v131, v133, v135
	v_cvt_pk_bf16_f32 v167, v134, v135
	s_mov_b32 m0, s11
	s_cmp_ge_u32 s22, s17
	s_cbranch_scc1 .LBB0_190
	global_load_lds_dwordx4 v214, s[80:81]
	s_add_i32 m0, s11, 0x2000
	s_nop 0
	global_load_lds_dwordx4 v214, s[62:63]

.LBB0_225:
	ds_read_b128 v[126:129], v244 offset:32768
	s_waitcnt lgkmcnt(1)
	v_mfma_f32_32x32x16_bf16 v[82:97], v[202:205], v[146:149], v[66:81]
	ds_read_b128 v[122:125], v240 offset:40960
	v_mfma_f32_32x32x16_bf16 v[98:113], v[194:197], v[146:149], v[66:81]
	ds_read_b128 v[114:117], v241 offset:32768
	v_mfma_f32_32x32x16_bf16 v[82:97], v[198:201], v[150:153], v[82:97]
	ds_read_b128 v[118:121], v241 offset:40960
	s_waitcnt lgkmcnt(0)
	v_mfma_f32_32x32x16_bf16 v[98:113], v[122:125], v[150:153], v[98:113]
	ds_read_b128 v[122:125], v243 offset:32768
	v_mfma_f32_32x32x16_bf16 v[82:97], v[114:117], v[154:157], v[82:97]
	ds_read_b128 v[114:117], v243 offset:40960
	v_mfma_f32_32x32x16_bf16 v[98:113], v[118:121], v[154:157], v[98:113]
	s_waitcnt lgkmcnt(0)
	v_mfma_f32_32x32x16_bf16 v[82:97], v[122:125], v[158:161], v[82:97]
	v_mfma_f32_32x32x16_bf16 v[98:113], v[114:117], v[158:161], v[98:113]
	s_nop 1
	ds_read_b128 v[122:125], v244 offset:36864
	ds_read_b128 v[118:121], v244 offset:40960
	ds_read_b128 v[114:117], v244 offset:45056
	s_add_i32 s26, s21, 0x80
	s_cmp_le_u32 s26, s20
	s_cbranch_scc0 .Lnear_u1o
.LBB0_228:
	v_mfma_f32_32x32x16_bf16 v[34:49], v[126:129], v[166:169], v[34:49]
	ds_read_b128 v[126:129], v245 offset:32768
	v_exp_f32_e32 v130, v82
	v_exp_f32_e32 v131, v83
	v_add_f32_e32 v132, v1, v130
	v_add_f32_e32 v133, v1, v131
	v_cvt_pk_bf16_f32 v162, v130, v131
	s_waitcnt lgkmcnt(3)
	v_mfma_f32_32x32x16_bf16 v[50:65], v[122:125], v[166:169], v[50:65]
	ds_read_b128 v[122:125], v245 offset:36864
	v_exp_f32_e32 v130, v84
	v_exp_f32_e32 v131, v85
	s_add_i32 s23, s23, 3
	v_add_f32_e32 v132, v132, v130
	v_add_f32_e32 v133, v133, v131
	v_cvt_pk_bf16_f32 v163, v130, v131
	s_add_i32 m0, s11, 0x4000
	s_cmp_gt_u32 s23, s16
	s_cbranch_scc1 .LBB0_230
	global_load_lds_dwordx4 v214, s[50:51]
	s_add_i32 m0, s11, 0x6000
	s_nop 0
	global_load_lds_dwordx4 v214, s[4:5]

.Lr1u1_LBB0_185:
	ds_read_b128 v[126:129], v244 offset:49152
	s_waitcnt lgkmcnt(1)
	v_mfma_f32_32x32x16_bf16 v[82:97], v[202:205], v[146:149], v[66:81]
	ds_read_b128 v[122:125], v240 offset:8192
	v_mfma_f32_32x32x16_bf16 v[98:113], v[194:197], v[146:149], v[66:81]
	ds_read_b128 v[114:117], v241
	v_mfma_f32_32x32x16_bf16 v[82:97], v[198:201], v[150:153], v[82:97]
	ds_read_b128 v[118:121], v241 offset:8192
	s_waitcnt lgkmcnt(0)
	v_mfma_f32_32x32x16_bf16 v[98:113], v[122:125], v[150:153], v[98:113]
	ds_read_b128 v[122:125], v243
	v_mfma_f32_32x32x16_bf16 v[82:97], v[114:117], v[154:157], v[82:97]
	ds_read_b128 v[114:117], v243 offset:8192
	v_mfma_f32_32x32x16_bf16 v[98:113], v[118:121], v[154:157], v[98:113]
	s_waitcnt lgkmcnt(0)
	v_mfma_f32_32x32x16_bf16 v[82:97], v[122:125], v[158:161], v[82:97]
	v_mfma_f32_32x32x16_bf16 v[98:113], v[114:117], v[158:161], v[98:113]
	s_nop 1
	ds_read_b128 v[122:125], v244 offset:53248
	ds_read_b128 v[118:121], v244 offset:57344
	ds_read_b128 v[114:117], v244 offset:61440
	s_add_i32 s22, s21, 64
	s_cmp_le_u32 s22, s20
	s_cbranch_scc0 .Lr1u1_Lnear_u1e
.Lr1u1_LBB0_188:
	v_mfma_f32_32x32x16_bf16 v[34:49], v[126:129], v[162:165], v[34:49]
	ds_read_b128 v[126:129], v245 offset:49152
	v_exp_f32_e32 v130, v82
	v_exp_f32_e32 v131, v83
	v_add_f32_e32 v132, v1, v130
	v_add_f32_e32 v133, v1, v131
	v_cvt_pk_bf16_f32 v166, v130, v131
	s_waitcnt lgkmcnt(3)
	v_mfma_f32_32x32x16_bf16 v[50:65], v[122:125], v[162:165], v[50:65]
	ds_read_b128 v[122:125], v245 offset:53248
	v_exp_f32_e32 v134, v84
	v_exp_f32_e32 v135, v85
	s_add_i32 s22, s23, 2
	v_add_f32_e32 v130, v132, v134
	v_add_f32_e32 v131, v133, v135
	v_cvt_pk_bf16_f32 v167, v134, v135
	s_add_i32 m0, s11, 0x8000
	s_cmp_ge_u32 s22, s17
	s_cbranch_scc1 .Lr1u1_LBB0_190
	global_load_lds_dwordx4 v214, s[80:81]
	s_add_i32 m0, s11, 0xa000
	s_nop 0
	global_load_lds_dwordx4 v214, s[62:63]

.Lr1u1_LBB0_225:
	ds_read_b128 v[126:129], v244 offset:16384
	s_waitcnt lgkmcnt(1)
	v_mfma_f32_32x32x16_bf16 v[82:97], v[202:205], v[146:149], v[66:81]
	ds_read_b128 v[122:125], v240 offset:24576
	v_mfma_f32_32x32x16_bf16 v[98:113], v[194:197], v[146:149], v[66:81]
	ds_read_b128 v[114:117], v241 offset:16384
	v_mfma_f32_32x32x16_bf16 v[82:97], v[198:201], v[150:153], v[82:97]
	ds_read_b128 v[118:121], v241 offset:24576
	s_waitcnt lgkmcnt(0)
	v_mfma_f32_32x32x16_bf16 v[98:113], v[122:125], v[150:153], v[98:113]
	ds_read_b128 v[122:125], v243 offset:16384
	v_mfma_f32_32x32x16_bf16 v[82:97], v[114:117], v[154:157], v[82:97]
	ds_read_b128 v[114:117], v243 offset:24576
	v_mfma_f32_32x32x16_bf16 v[98:113], v[118:121], v[154:157], v[98:113]
	s_waitcnt lgkmcnt(0)
	v_mfma_f32_32x32x16_bf16 v[82:97], v[122:125], v[158:161], v[82:97]
	v_mfma_f32_32x32x16_bf16 v[98:113], v[114:117], v[158:161], v[98:113]
	s_nop 1
	ds_read_b128 v[122:125], v244 offset:20480
	ds_read_b128 v[118:121], v244 offset:24576
	ds_read_b128 v[114:117], v244 offset:28672
	s_add_i32 s26, s21, 0x80
	s_cmp_le_u32 s26, s20
	s_cbranch_scc0 .Lr1u1_Lnear_u1o
.Lr1u1_LBB0_228:
	v_mfma_f32_32x32x16_bf16 v[34:49], v[126:129], v[166:169], v[34:49]
	ds_read_b128 v[126:129], v245 offset:16384
	v_exp_f32_e32 v130, v82
	v_exp_f32_e32 v131, v83
	v_add_f32_e32 v132, v1, v130
	v_add_f32_e32 v133, v1, v131
	v_cvt_pk_bf16_f32 v162, v130, v131
	s_waitcnt lgkmcnt(3)
	v_mfma_f32_32x32x16_bf16 v[50:65], v[122:125], v[166:169], v[50:65]
	ds_read_b128 v[122:125], v245 offset:20480
	v_exp_f32_e32 v130, v84
	v_exp_f32_e32 v131, v85
	s_add_i32 s23, s23, 3
	v_add_f32_e32 v132, v132, v130
	v_add_f32_e32 v133, v133, v131
	v_cvt_pk_bf16_f32 v163, v130, v131
	s_mov_b32 m0, s11
	s_cmp_gt_u32 s23, s16
	s_cbranch_scc1 .Lr1u1_LBB0_230
	global_load_lds_dwordx4 v214, s[50:51]
	s_add_i32 m0, s11, 0x2000
	s_nop 0
	global_load_lds_dwordx4 v214, s[4:5]

.Lr2u1_LBB0_185:
	ds_read_b128 v[126:129], v244 offset:32768
	s_waitcnt lgkmcnt(1)
	v_mfma_f32_32x32x16_bf16 v[82:97], v[202:205], v[146:149], v[66:81]
	ds_read_b128 v[122:125], v240 offset:40960
	v_mfma_f32_32x32x16_bf16 v[98:113], v[194:197], v[146:149], v[66:81]
	ds_read_b128 v[114:117], v241 offset:32768
	v_mfma_f32_32x32x16_bf16 v[82:97], v[198:201], v[150:153], v[82:97]
	ds_read_b128 v[118:121], v241 offset:40960
	s_waitcnt lgkmcnt(0)
	v_mfma_f32_32x32x16_bf16 v[98:113], v[122:125], v[150:153], v[98:113]
	ds_read_b128 v[122:125], v243 offset:32768
	v_mfma_f32_32x32x16_bf16 v[82:97], v[114:117], v[154:157], v[82:97]
	ds_read_b128 v[114:117], v243 offset:40960
	v_mfma_f32_32x32x16_bf16 v[98:113], v[118:121], v[154:157], v[98:113]
	s_waitcnt lgkmcnt(0)
	v_mfma_f32_32x32x16_bf16 v[82:97], v[122:125], v[158:161], v[82:97]
	v_mfma_f32_32x32x16_bf16 v[98:113], v[114:117], v[158:161], v[98:113]
	s_nop 1
	ds_read_b128 v[122:125], v244 offset:36864
	ds_read_b128 v[118:121], v244 offset:40960
	ds_read_b128 v[114:117], v244 offset:45056
	s_add_i32 s22, s21, 64
	s_cmp_le_u32 s22, s20
	s_cbranch_scc0 .Lr2u1_Lnear_u1e
.Lr2u1_LBB0_188:
	v_mfma_f32_32x32x16_bf16 v[34:49], v[126:129], v[162:165], v[34:49]
	ds_read_b128 v[126:129], v245 offset:32768
	v_exp_f32_e32 v130, v82
	v_exp_f32_e32 v131, v83
	v_add_f32_e32 v132, v1, v130
	v_add_f32_e32 v133, v1, v131
	v_cvt_pk_bf16_f32 v166, v130, v131
	s_waitcnt lgkmcnt(3)
	v_mfma_f32_32x32x16_bf16 v[50:65], v[122:125], v[162:165], v[50:65]
	ds_read_b128 v[122:125], v245 offset:36864
	v_exp_f32_e32 v134, v84
	v_exp_f32_e32 v135, v85
	s_add_i32 s22, s23, 2
	v_add_f32_e32 v130, v132, v134
	v_add_f32_e32 v131, v133, v135
	v_cvt_pk_bf16_f32 v167, v134, v135
	s_add_i32 m0, s11, 0x4000
	s_cmp_ge_u32 s22, s17
	s_cbranch_scc1 .Lr2u1_LBB0_190
	global_load_lds_dwordx4 v214, s[80:81]
	s_add_i32 m0, s11, 0x6000
	s_nop 0
	global_load_lds_dwordx4 v214, s[62:63]

.Lr2u1_LBB0_225:
	ds_read_b128 v[126:129], v244 offset:49152
	s_waitcnt lgkmcnt(1)
	v_mfma_f32_32x32x16_bf16 v[82:97], v[202:205], v[146:149], v[66:81]
	ds_read_b128 v[122:125], v240 offset:8192
	v_mfma_f32_32x32x16_bf16 v[98:113], v[194:197], v[146:149], v[66:81]
	ds_read_b128 v[114:117], v241
	v_mfma_f32_32x32x16_bf16 v[82:97], v[198:201], v[150:153], v[82:97]
	ds_read_b128 v[118:121], v241 offset:8192
	s_waitcnt lgkmcnt(0)
	v_mfma_f32_32x32x16_bf16 v[98:113], v[122:125], v[150:153], v[98:113]
	ds_read_b128 v[122:125], v243
	v_mfma_f32_32x32x16_bf16 v[82:97], v[114:117], v[154:157], v[82:97]
	ds_read_b128 v[114:117], v243 offset:8192
	v_mfma_f32_32x32x16_bf16 v[98:113], v[118:121], v[154:157], v[98:113]
	s_waitcnt lgkmcnt(0)
	v_mfma_f32_32x32x16_bf16 v[82:97], v[122:125], v[158:161], v[82:97]
	v_mfma_f32_32x32x16_bf16 v[98:113], v[114:117], v[158:161], v[98:113]
	s_nop 1
	ds_read_b128 v[122:125], v244 offset:53248
	ds_read_b128 v[118:121], v244 offset:57344
	ds_read_b128 v[114:117], v244 offset:61440
	s_add_i32 s26, s21, 0x80
	s_cmp_le_u32 s26, s20
	s_cbranch_scc0 .Lr2u1_Lnear_u1o
.Lr2u1_LBB0_228:
	v_mfma_f32_32x32x16_bf16 v[34:49], v[126:129], v[166:169], v[34:49]
	ds_read_b128 v[126:129], v245 offset:49152
	v_exp_f32_e32 v130, v82
	v_exp_f32_e32 v131, v83
	v_add_f32_e32 v132, v1, v130
	v_add_f32_e32 v133, v1, v131
	v_cvt_pk_bf16_f32 v162, v130, v131
	s_waitcnt lgkmcnt(3)
	v_mfma_f32_32x32x16_bf16 v[50:65], v[122:125], v[166:169], v[50:65]
	ds_read_b128 v[122:125], v245 offset:53248
	v_exp_f32_e32 v130, v84
	v_exp_f32_e32 v131, v85
	s_add_i32 s23, s23, 3
	v_add_f32_e32 v132, v132, v130
	v_add_f32_e32 v133, v133, v131
	v_cvt_pk_bf16_f32 v163, v130, v131
	s_add_i32 m0, s11, 0x8000
	s_cmp_gt_u32 s23, s16
	s_cbranch_scc1 .Lr2u1_LBB0_230
	global_load_lds_dwordx4 v214, s[50:51]
	s_add_i32 m0, s11, 0xa000
	s_nop 0
	global_load_lds_dwordx4 v214, s[4:5]

.LBB0_288:
	ds_read_b128 v[126:129], v245 offset:16384
	s_waitcnt lgkmcnt(1)
	v_mfma_f32_32x32x16_bf16 v[82:97], v[202:205], v[146:149], v[66:81]
	ds_read_b128 v[122:125], v240 offset:24576
	v_mfma_f32_32x32x16_bf16 v[98:113], v[194:197], v[146:149], v[66:81]
	ds_read_b128 v[114:117], v241 offset:16384
	v_mfma_f32_32x32x16_bf16 v[82:97], v[198:201], v[150:153], v[82:97]
	ds_read_b128 v[118:121], v241 offset:24576
	s_waitcnt lgkmcnt(0)
	v_mfma_f32_32x32x16_bf16 v[98:113], v[122:125], v[150:153], v[98:113]
	ds_read_b128 v[122:125], v242 offset:16384
	v_mfma_f32_32x32x16_bf16 v[82:97], v[114:117], v[154:157], v[82:97]
	ds_read_b128 v[114:117], v242 offset:24576
	v_mfma_f32_32x32x16_bf16 v[98:113], v[118:121], v[154:157], v[98:113]
	s_waitcnt lgkmcnt(0)
	v_mfma_f32_32x32x16_bf16 v[82:97], v[122:125], v[158:161], v[82:97]
	v_mfma_f32_32x32x16_bf16 v[98:113], v[114:117], v[158:161], v[98:113]
	s_nop 2
	ds_read_b128 v[122:125], v245 offset:20480
	ds_read_b128 v[118:121], v245 offset:24576
	ds_read_b128 v[114:117], v245 offset:28672
	s_cmp_le_u32 s20, s16
	s_cbranch_scc0 .Lnear_u2e
.LBB0_291:
	v_mfma_f32_32x32x16_bf16 v[50:65], v[126:129], v[162:165], v[50:65]
	ds_read_b128 v[126:129], v246 offset:16384
	v_exp_f32_e32 v130, v82
	v_exp_f32_e32 v131, v83
	v_add_f32_e32 v132, v1, v130
	v_add_f32_e32 v133, v1, v131
	v_cvt_pk_bf16_f32 v166, v130, v131
	s_waitcnt lgkmcnt(3)
	v_mfma_f32_32x32x16_bf16 v[34:49], v[122:125], v[162:165], v[34:49]
	ds_read_b128 v[122:125], v246 offset:20480
	v_exp_f32_e32 v134, v84
	v_exp_f32_e32 v135, v85
	s_add_i32 s21, s22, 2
	v_add_f32_e32 v130, v132, v134
	v_add_f32_e32 v131, v133, v135
	v_cvt_pk_bf16_f32 v167, v134, v135
	s_mov_b32 m0, s10
	s_cmp_ge_u32 s21, s18
	s_cbranch_scc1 .LBB0_293
	global_load_lds_dwordx4 v214, s[80:81]
	s_add_i32 m0, s10, 0x2000
	s_nop 0
	global_load_lds_dwordx4 v214, s[62:63]

.LBB0_328:
	ds_read_b128 v[126:129], v245 offset:32768
	s_waitcnt lgkmcnt(1)
	v_mfma_f32_32x32x16_bf16 v[82:97], v[202:205], v[146:149], v[66:81]
	ds_read_b128 v[122:125], v240 offset:40960
	v_mfma_f32_32x32x16_bf16 v[98:113], v[194:197], v[146:149], v[66:81]
	ds_read_b128 v[114:117], v241 offset:32768
	v_mfma_f32_32x32x16_bf16 v[82:97], v[198:201], v[150:153], v[82:97]
	ds_read_b128 v[118:121], v241 offset:40960
	s_waitcnt lgkmcnt(0)
	v_mfma_f32_32x32x16_bf16 v[98:113], v[122:125], v[150:153], v[98:113]
	ds_read_b128 v[122:125], v242 offset:32768
	v_mfma_f32_32x32x16_bf16 v[82:97], v[114:117], v[154:157], v[82:97]
	ds_read_b128 v[114:117], v242 offset:40960
	v_mfma_f32_32x32x16_bf16 v[98:113], v[118:121], v[154:157], v[98:113]
	s_waitcnt lgkmcnt(0)
	v_mfma_f32_32x32x16_bf16 v[82:97], v[122:125], v[158:161], v[82:97]
	v_mfma_f32_32x32x16_bf16 v[98:113], v[114:117], v[158:161], v[98:113]
	s_nop 1
	ds_read_b128 v[122:125], v245 offset:36864
	ds_read_b128 v[118:121], v245 offset:40960
	ds_read_b128 v[114:117], v245 offset:45056
	s_add_i32 s26, s20, 64
	s_cmp_le_u32 s26, s16
	s_cbranch_scc0 .Lnear_u2o
.LBB0_331:
	v_mfma_f32_32x32x16_bf16 v[50:65], v[126:129], v[166:169], v[50:65]
	ds_read_b128 v[126:129], v246 offset:32768
	v_exp_f32_e32 v130, v82
	v_exp_f32_e32 v131, v83
	v_add_f32_e32 v132, v1, v130
	v_add_f32_e32 v133, v1, v131
	v_cvt_pk_bf16_f32 v162, v130, v131
	s_waitcnt lgkmcnt(3)
	v_mfma_f32_32x32x16_bf16 v[34:49], v[122:125], v[166:169], v[34:49]
	ds_read_b128 v[122:125], v246 offset:36864
	v_exp_f32_e32 v130, v84
	v_exp_f32_e32 v131, v85
	s_add_i32 s22, s22, 3
	v_add_f32_e32 v132, v132, v130
	v_add_f32_e32 v133, v133, v131
	v_cvt_pk_bf16_f32 v163, v130, v131
	s_add_i32 m0, s10, 0x4000
	s_cmp_gt_u32 s22, s17
	s_cbranch_scc1 .LBB0_333
	global_load_lds_dwordx4 v214, s[50:51]
	s_add_i32 m0, s10, 0x6000
	s_nop 0
	global_load_lds_dwordx4 v214, s[4:5]

.Lr1u2_LBB0_288:
	ds_read_b128 v[126:129], v245 offset:49152
	s_waitcnt lgkmcnt(1)
	v_mfma_f32_32x32x16_bf16 v[82:97], v[202:205], v[146:149], v[66:81]
	ds_read_b128 v[122:125], v240 offset:8192
	v_mfma_f32_32x32x16_bf16 v[98:113], v[194:197], v[146:149], v[66:81]
	ds_read_b128 v[114:117], v241
	v_mfma_f32_32x32x16_bf16 v[82:97], v[198:201], v[150:153], v[82:97]
	ds_read_b128 v[118:121], v241 offset:8192
	s_waitcnt lgkmcnt(0)
	v_mfma_f32_32x32x16_bf16 v[98:113], v[122:125], v[150:153], v[98:113]
	ds_read_b128 v[122:125], v242
	v_mfma_f32_32x32x16_bf16 v[82:97], v[114:117], v[154:157], v[82:97]
	ds_read_b128 v[114:117], v242 offset:8192
	v_mfma_f32_32x32x16_bf16 v[98:113], v[118:121], v[154:157], v[98:113]
	s_waitcnt lgkmcnt(0)
	v_mfma_f32_32x32x16_bf16 v[82:97], v[122:125], v[158:161], v[82:97]
	v_mfma_f32_32x32x16_bf16 v[98:113], v[114:117], v[158:161], v[98:113]
	s_nop 2
	ds_read_b128 v[122:125], v245 offset:53248
	ds_read_b128 v[118:121], v245 offset:57344
	ds_read_b128 v[114:117], v245 offset:61440
	s_cmp_le_u32 s20, s16
	s_cbranch_scc0 .Lr1u2_Lnear_u2e
.Lr1u2_LBB0_291:
	v_mfma_f32_32x32x16_bf16 v[50:65], v[126:129], v[162:165], v[50:65]
	ds_read_b128 v[126:129], v246 offset:49152
	v_exp_f32_e32 v130, v82
	v_exp_f32_e32 v131, v83
	v_add_f32_e32 v132, v1, v130
	v_add_f32_e32 v133, v1, v131
	v_cvt_pk_bf16_f32 v166, v130, v131
	s_waitcnt lgkmcnt(3)
	v_mfma_f32_32x32x16_bf16 v[34:49], v[122:125], v[162:165], v[34:49]
	ds_read_b128 v[122:125], v246 offset:53248
	v_exp_f32_e32 v134, v84
	v_exp_f32_e32 v135, v85
	s_add_i32 s21, s22, 2
	v_add_f32_e32 v130, v132, v134
	v_add_f32_e32 v131, v133, v135
	v_cvt_pk_bf16_f32 v167, v134, v135
	s_add_i32 m0, s10, 0x8000
	s_cmp_ge_u32 s21, s18
	s_cbranch_scc1 .Lr1u2_LBB0_293
	global_load_lds_dwordx4 v214, s[80:81]
	s_add_i32 m0, s10, 0xa000
	s_nop 0
	global_load_lds_dwordx4 v214, s[62:63]

.Lr1u2_LBB0_328:
	ds_read_b128 v[126:129], v245 offset:16384
	s_waitcnt lgkmcnt(1)
	v_mfma_f32_32x32x16_bf16 v[82:97], v[202:205], v[146:149], v[66:81]
	ds_read_b128 v[122:125], v240 offset:24576
	v_mfma_f32_32x32x16_bf16 v[98:113], v[194:197], v[146:149], v[66:81]
	ds_read_b128 v[114:117], v241 offset:16384
	v_mfma_f32_32x32x16_bf16 v[82:97], v[198:201], v[150:153], v[82:97]
	ds_read_b128 v[118:121], v241 offset:24576
	s_waitcnt lgkmcnt(0)
	v_mfma_f32_32x32x16_bf16 v[98:113], v[122:125], v[150:153], v[98:113]
	ds_read_b128 v[122:125], v242 offset:16384
	v_mfma_f32_32x32x16_bf16 v[82:97], v[114:117], v[154:157], v[82:97]
	ds_read_b128 v[114:117], v242 offset:24576
	v_mfma_f32_32x32x16_bf16 v[98:113], v[118:121], v[154:157], v[98:113]
	s_waitcnt lgkmcnt(0)
	v_mfma_f32_32x32x16_bf16 v[82:97], v[122:125], v[158:161], v[82:97]
	v_mfma_f32_32x32x16_bf16 v[98:113], v[114:117], v[158:161], v[98:113]
	s_nop 1
	ds_read_b128 v[122:125], v245 offset:20480
	ds_read_b128 v[118:121], v245 offset:24576
	ds_read_b128 v[114:117], v245 offset:28672
	s_add_i32 s26, s20, 64
	s_cmp_le_u32 s26, s16
	s_cbranch_scc0 .Lr1u2_Lnear_u2o
.Lr1u2_LBB0_331:
	v_mfma_f32_32x32x16_bf16 v[50:65], v[126:129], v[166:169], v[50:65]
	ds_read_b128 v[126:129], v246 offset:16384
	v_exp_f32_e32 v130, v82
	v_exp_f32_e32 v131, v83
	v_add_f32_e32 v132, v1, v130
	v_add_f32_e32 v133, v1, v131
	v_cvt_pk_bf16_f32 v162, v130, v131
	s_waitcnt lgkmcnt(3)
	v_mfma_f32_32x32x16_bf16 v[34:49], v[122:125], v[166:169], v[34:49]
	ds_read_b128 v[122:125], v246 offset:20480
	v_exp_f32_e32 v130, v84
	v_exp_f32_e32 v131, v85
	s_add_i32 s22, s22, 3
	v_add_f32_e32 v132, v132, v130
	v_add_f32_e32 v133, v133, v131
	v_cvt_pk_bf16_f32 v163, v130, v131
	s_mov_b32 m0, s10
	s_cmp_gt_u32 s22, s17
	s_cbranch_scc1 .Lr1u2_LBB0_333
	global_load_lds_dwordx4 v214, s[50:51]
	s_add_i32 m0, s10, 0x2000
	s_nop 0
	global_load_lds_dwordx4 v214, s[4:5]

.Lr2u2_LBB0_288:
	ds_read_b128 v[126:129], v245 offset:32768
	s_waitcnt lgkmcnt(1)
	v_mfma_f32_32x32x16_bf16 v[82:97], v[202:205], v[146:149], v[66:81]
	ds_read_b128 v[122:125], v240 offset:40960
	v_mfma_f32_32x32x16_bf16 v[98:113], v[194:197], v[146:149], v[66:81]
	ds_read_b128 v[114:117], v241 offset:32768
	v_mfma_f32_32x32x16_bf16 v[82:97], v[198:201], v[150:153], v[82:97]
	ds_read_b128 v[118:121], v241 offset:40960
	s_waitcnt lgkmcnt(0)
	v_mfma_f32_32x32x16_bf16 v[98:113], v[122:125], v[150:153], v[98:113]
	ds_read_b128 v[122:125], v242 offset:32768
	v_mfma_f32_32x32x16_bf16 v[82:97], v[114:117], v[154:157], v[82:97]
	ds_read_b128 v[114:117], v242 offset:40960
	v_mfma_f32_32x32x16_bf16 v[98:113], v[118:121], v[154:157], v[98:113]
	s_waitcnt lgkmcnt(0)
	v_mfma_f32_32x32x16_bf16 v[82:97], v[122:125], v[158:161], v[82:97]
	v_mfma_f32_32x32x16_bf16 v[98:113], v[114:117], v[158:161], v[98:113]
	s_nop 2
	ds_read_b128 v[122:125], v245 offset:36864
	ds_read_b128 v[118:121], v245 offset:40960
	ds_read_b128 v[114:117], v245 offset:45056
	s_cmp_le_u32 s20, s16
	s_cbranch_scc0 .Lr2u2_Lnear_u2e
.Lr2u2_LBB0_291:
	v_mfma_f32_32x32x16_bf16 v[50:65], v[126:129], v[162:165], v[50:65]
	ds_read_b128 v[126:129], v246 offset:32768
	v_exp_f32_e32 v130, v82
	v_exp_f32_e32 v131, v83
	v_add_f32_e32 v132, v1, v130
	v_add_f32_e32 v133, v1, v131
	v_cvt_pk_bf16_f32 v166, v130, v131
	s_waitcnt lgkmcnt(3)
	v_mfma_f32_32x32x16_bf16 v[34:49], v[122:125], v[162:165], v[34:49]
	ds_read_b128 v[122:125], v246 offset:36864
	v_exp_f32_e32 v134, v84
	v_exp_f32_e32 v135, v85
	s_add_i32 s21, s22, 2
	v_add_f32_e32 v130, v132, v134
	v_add_f32_e32 v131, v133, v135
	v_cvt_pk_bf16_f32 v167, v134, v135
	s_add_i32 m0, s10, 0x4000
	s_cmp_ge_u32 s21, s18
	s_cbranch_scc1 .Lr2u2_LBB0_293
	global_load_lds_dwordx4 v214, s[80:81]
	s_add_i32 m0, s10, 0x6000
	s_nop 0
	global_load_lds_dwordx4 v214, s[62:63]

.Lr2u2_LBB0_328:
	ds_read_b128 v[126:129], v245 offset:49152
	s_waitcnt lgkmcnt(1)
	v_mfma_f32_32x32x16_bf16 v[82:97], v[202:205], v[146:149], v[66:81]
	ds_read_b128 v[122:125], v240 offset:8192
	v_mfma_f32_32x32x16_bf16 v[98:113], v[194:197], v[146:149], v[66:81]
	ds_read_b128 v[114:117], v241
	v_mfma_f32_32x32x16_bf16 v[82:97], v[198:201], v[150:153], v[82:97]
	ds_read_b128 v[118:121], v241 offset:8192
	s_waitcnt lgkmcnt(0)
	v_mfma_f32_32x32x16_bf16 v[98:113], v[122:125], v[150:153], v[98:113]
	ds_read_b128 v[122:125], v242
	v_mfma_f32_32x32x16_bf16 v[82:97], v[114:117], v[154:157], v[82:97]
	ds_read_b128 v[114:117], v242 offset:8192
	v_mfma_f32_32x32x16_bf16 v[98:113], v[118:121], v[154:157], v[98:113]
	s_waitcnt lgkmcnt(0)
	v_mfma_f32_32x32x16_bf16 v[82:97], v[122:125], v[158:161], v[82:97]
	v_mfma_f32_32x32x16_bf16 v[98:113], v[114:117], v[158:161], v[98:113]
	s_nop 1
	ds_read_b128 v[122:125], v245 offset:53248
	ds_read_b128 v[118:121], v245 offset:57344
	ds_read_b128 v[114:117], v245 offset:61440
	s_add_i32 s26, s20, 64
	s_cmp_le_u32 s26, s16
	s_cbranch_scc0 .Lr2u2_Lnear_u2o
.Lr2u2_LBB0_331:
	v_mfma_f32_32x32x16_bf16 v[50:65], v[126:129], v[166:169], v[50:65]
	ds_read_b128 v[126:129], v246 offset:49152
	v_exp_f32_e32 v130, v82
	v_exp_f32_e32 v131, v83
	v_add_f32_e32 v132, v1, v130
	v_add_f32_e32 v133, v1, v131
	v_cvt_pk_bf16_f32 v162, v130, v131
	s_waitcnt lgkmcnt(3)
	v_mfma_f32_32x32x16_bf16 v[34:49], v[122:125], v[166:169], v[34:49]
	ds_read_b128 v[122:125], v246 offset:53248
	v_exp_f32_e32 v130, v84
	v_exp_f32_e32 v131, v85
	s_add_i32 s22, s22, 3
	v_add_f32_e32 v132, v132, v130
	v_add_f32_e32 v133, v133, v131
	v_cvt_pk_bf16_f32 v163, v130, v131
	s_add_i32 m0, s10, 0x8000
	s_cmp_gt_u32 s22, s17
	s_cbranch_scc1 .Lr2u2_LBB0_333
	global_load_lds_dwordx4 v214, s[50:51]
	s_add_i32 m0, s10, 0xa000
	s_nop 0
	global_load_lds_dwordx4 v214, s[4:5]
